# e23: e18 + GLU GEMM units fetch their eight silu(z) quads before the K loop (next unit's behind the stores) instead of cold in the epilogue
# baseline (speedup 1.0000x reference)
; #define PG8_STAGE_A(bufoff, gbase) PG8_STAGE(bufoff, gbase, voffA, a64)
; #define PG8_STAGE_B(bufoff, bp, hb, tz) do { if (BMODE == 1 && (tz)) PG8_STAGE(bufoff, (bp) + (hb) * 4096, voffT, t64); else PG8_STAGE(bufoff, (bp) + (hb) * bhstep, voffB, b64); } while (0)
; #define PG8_WAIT_V(n) asm volatile("s_waitcnt vmcnt(" #n ")" ::: "memory")
; #define PG8_BAR __builtin_amdgcn_s_barrier()
; template <class CF, class Epi, class Sched, bool ALIGN_EPI, bool SP2>
; __device__ __forceinline__ void gemm_phase(LAS unsigned char* lds, const char* gA, const char* gB, const Sched& S, const Epi& E, const char* gB2 = nullptr) {
;     ...
;     const char* cA = gA + (size_t)cur.g * CF::A_G + (size_t)cur.pm * CF::A_T; const char* cB = gB + (size_t)cur.g * CF::B_G + (size_t)cur.pn * CF::B_T;
;     const char* cT = BMODE == 1 ? gB2 + (size_t)cur.g * KTG + (size_t)cur.pn * 8192 + 14336 : nullptr;
;     PG8_STAGE_B(PG8_SB(0, 0), cB, 0, false); PG8_STAGE_B(PG8_SB(0, 1), cB, 1, false); PG8_STAGE_A(PG8_SA(0, 0), cA); PG8_STAGE_A(PG8_SA(0, 1), cA + ahstep);
;     if (wr == 1) PG8_BAR;
;     PG8_WAIT_V(2); PG8_BAR;
;     PG8_STAGE_B(PG8_SB(1, 0), cB + bkstep, 0, false); PG8_STAGE_A(PG8_SA(1, 0), cA + akstep); PG8_STAGE_B(PG8_SB(1, 1), cB + bkstep, 1, false);
;     PG8_WAIT_V(6); PG8_BAR;
;     __device__ __forceinline__ void operator()(AccRef acc, const Unit& u, int wr, int wc, int fr, int fq) const {
;         int row0 = u.pm * 256 + wr * 64 + fr; asm volatile("" : "+v"(row0)); int col0 = u.pn * 128 + wc * 32 + 8 * fq; asm volatile("" : "+v"(col0));
;         const f32x4 b10 = *(const f32x4*)(gb + col0), b11 = *(const f32x4*)(gb + col0 + 4), b20 = *(const f32x4*)(gb + SW + col0), b21 = *(const f32x4*)(gb + SW + col0 + 4);
;         u32x4 zv[2][4];
; #pragma unroll
;         for (int ai = 0; ai < 2; ++ai)
; #pragma unroll
;             for (int m = 0; m < 4; ++m) zv[ai][m] = *(const u32x4*)(zs + (size_t)(row0 + ai * HALF + m * 16) * D + PW + col0);
.LBB0_1060:
	s_add_u32 s26, s50, 0x19800000
	s_addc_u32 s27, s51, 0
	s_add_u32 s28, s50, 0xf600000
	s_mov_b64 s[30:31], 0x80
	s_addc_u32 s29, s51, 0
	v_lshl_add_u64 v[10:11], v[2:3], 0, s[30:31]
	s_add_i32 m0, s73, 0x18000
	s_mov_b64 s[34:35], 0x20080
	s_waitcnt vmcnt(2)
	s_barrier
	global_load_lds_dwordx4 v[10:11], off
	v_lshl_add_u64 v[10:11], v[2:3], 0, s[34:35]
	s_add_i32 m0, s73, 0x1a000
	s_add_i32 s84, s73, 0x8000
	global_load_lds_dwordx4 v[10:11], off
	v_lshl_add_u64 v[10:11], v[4:5], 0, s[8:9]
	s_mov_b32 m0, s84
	s_mov_b64 s[36:37], 0x200800
	s_add_i32 s85, s73, 0xa000
	global_load_lds_dwordx4 v[10:11], off
	v_lshl_add_u64 v[4:5], v[4:5], 0, s[36:37]
	s_mov_b32 m0, s85
	s_mov_b64 s[38:39], 0x200080
	global_load_lds_dwordx4 v[4:5], off
	v_lshl_add_u64 v[4:5], v[2:3], 0, s[38:39]
	s_add_i32 m0, s73, 0x1c000
	s_mov_b64 s[40:41], 0x220080
	global_load_lds_dwordx4 v[4:5], off
	v_lshl_add_u64 v[2:3], v[2:3], 0, s[40:41]
	s_add_i32 m0, s73, 0x1e000
	v_lshlrev_b32_e32 v4, 2, v0
	global_load_lds_dwordx4 v[2:3], off
	v_and_b32_e32 v2, 15, v0
	v_lshlrev_b32_e32 v3, 1, v9
	v_lshl_or_b32 v1, s3, 6, v2
	v_lshl_or_b32 v2, v2, 6, v3
	s_lshl_b32 s3, s3, 13
	v_and_b32_e32 v5, 32, v4
	s_lshl_b32 s2, s2, 5
	v_bitop3_b32 v2, v2, s3, v5 bitop3:0xde
	s_and_b32 s2, s2, 0x60
	v_lshlrev_b32_e32 v10, 6, v0
	s_movk_i32 s3, 0x3c0
	v_and_or_b32 v3, v10, s3, v3
	s_lshl_b32 s3, s2, 7
	s_cmpk_lt_u32 s18, 0x100
	v_bitop3_b32 v194, s3, v3, v5 bitop3:0xf6
	s_cselect_b64 s[44:45], -1, 0
	s_ashr_i32 s86, s17, 31
	v_or_b32_e32 v195, s2, v9
	v_lshlrev_b32_e32 v3, 14, v0
	v_lshlrev_b32_e32 v5, 14, v7
	s_mov_b32 s2, 0x100000
	s_waitcnt vmcnt(6)
	s_add_u32 s54, s42, 0x1000
	v_and_or_b32 v3, v3, s2, v5
	s_mov_b32 s2, 0x180600
	s_addc_u32 s55, s43, 0
	v_bitop3_b32 v3, v3, s2, v4 bitop3:0xc8
	v_lshlrev_b32_e32 v4, 5, v6
	s_add_i32 s87, 0, 0x10000
	s_add_i32 s88, 0, 0x14000
	v_or3_b32 v174, v3, v4, v8
	v_mov_b32_e32 v175, v173
	v_mov_b64_e32 v[176:177], 0x200
	v_mov_b64_e32 v[178:179], 0x1ff
	v_add_u32_e32 v196, s87, v194
	v_add_u32_e32 v197, s88, v194
	v_add_u32_e32 v198, 0, v2
	s_mov_b64 s[56:57], 0x80000
	s_mov_b64 s[58:59], 0x90000
	s_mov_b64 s[60:61], 0xa0000
	s_mov_b64 s[62:63], 0xb0000
	v_lshl_add_u32 v250, s74, 8, v1
	v_lshl_or_b32 v252, s72, 7, v195
	v_lshlrev_b32_e32 v250, 12, v250
	v_lshl_add_u32 v250, v252, 1, v250
	global_load_dwordx4 v[218:221], v250, s[28:29] offset:2048
	s_add_u32 s98, s28, 0x10000
	s_addc_u32 s99, s29, 0
	global_load_dwordx4 v[222:225], v250, s[98:99] offset:2048
	s_add_u32 s98, s28, 0x20000
	s_addc_u32 s99, s29, 0
	global_load_dwordx4 v[226:229], v250, s[98:99] offset:2048
	s_add_u32 s98, s28, 0x30000
	s_addc_u32 s99, s29, 0
	global_load_dwordx4 v[230:233], v250, s[98:99] offset:2048
	s_add_u32 s98, s28, 0x80000
	s_addc_u32 s99, s29, 0
	global_load_dwordx4 v[234:237], v250, s[98:99] offset:2048
	s_add_u32 s98, s28, 0x90000
	s_addc_u32 s99, s29, 0
	global_load_dwordx4 v[238:241], v250, s[98:99] offset:2048
	s_add_u32 s98, s28, 0xa0000
	s_addc_u32 s99, s29, 0
	global_load_dwordx4 v[242:245], v250, s[98:99] offset:2048
	s_add_u32 s98, s28, 0xb0000
	s_addc_u32 s99, s29, 0
	global_load_dwordx4 v[246:249], v250, s[98:99] offset:2048
	s_barrier
	s_branch .LBB0_1063

; __device__ __forceinline__ float fast_sigmoid(float v) { return __builtin_amdgcn_rcpf(1.f + __expf(-v)); }
; __device__ __forceinline__ u32x4 pack8(const f32x4 v0, const f32x4 v1) { u32x4 w; w.x = pk_f16(v0[0], v0[1]); w.y = pk_f16(v0[2], v0[3]); w.z = pk_f16(v1[0], v1[1]); w.w = pk_f16(v1[2], v1[3]); return w; }
; __device__ __forceinline__ void unpack8(const u32x4 w, f32x4& v0, f32x4& v1) { v0 = (f32x4){f16lo(w.x), f16hi(w.x), f16lo(w.y), f16hi(w.y)}; v1 = (f32x4){f16lo(w.z), f16hi(w.z), f16lo(w.w), f16hi(w.w)}; }
;     __device__ __forceinline__ void operator()(AccRef acc, const Unit& u, int wr, int wc, int fr, int fq) const {
;         int row0 = u.pm * 256 + wr * 64 + fr; asm volatile("" : "+v"(row0)); int col0 = u.pn * 128 + wc * 32 + 8 * fq; asm volatile("" : "+v"(col0));
;         const f32x4 b10 = *(const f32x4*)(gb + col0), b11 = *(const f32x4*)(gb + col0 + 4), b20 = *(const f32x4*)(gb + SW + col0), b21 = *(const f32x4*)(gb + SW + col0 + 4);
;         u32x4 zv[2][4];
; #pragma unroll
;         for (int ai = 0; ai < 2; ++ai)
; #pragma unroll
;             for (int m = 0; m < 4; ++m) zv[ai][m] = *(const u32x4*)(zs + (size_t)(row0 + ai * HALF + m * 16) * D + PW + col0);
;         __builtin_amdgcn_sched_barrier(0);
; #pragma unroll
;         for (int ai = 0; ai < 2; ++ai)
; #pragma unroll
;             for (int m = 0; m < 4; ++m) { const size_t o = (size_t)(row0 + ai * HALF + m * 16) * D + PW + col0;
;                 f32x4 z0, z1; unpack8(zv[ai][m], z0, z1);
;                 f32x4 y10 = acc[ai][0][m][0] + b10, y11 = acc[ai][0][m][1] + b11, y20 = acc[ai][1][m][0] + b20, y21 = acc[ai][1][m][1] + b21;
; #pragma unroll
;                 for (int j = 0; j < 4; ++j) { y10[j] = y10[j] * fast_sigmoid(y20[j]) * z0[j]; y11[j] = y11[j] * fast_sigmoid(y21[j]) * z1[j]; }
;                 *(u32x4*)(branch + o) = pack8(y10, y11); }
.LBB0_1073:
	v_lshl_add_u32 v130, s74, 8, v1
	v_lshl_or_b32 v132, s72, 7, v195
	v_ashrrev_i32_e32 v131, 31, v130
	v_lshlrev_b64 v[208:209], 12, v[130:131]
	s_mov_b64 s[18:19], 0x10000
	v_lshl_add_u64 v[210:211], v[208:209], 0, s[18:19]
	v_ashrrev_i32_e32 v133, 31, v132
	v_lshlrev_b64 v[122:123], 2, v[132:133]
	v_lshl_add_u64 v[130:131], s[28:29], 0, v[208:209]
	v_lshlrev_b64 v[180:181], 1, v[132:133]
	v_lshl_add_u64 v[132:133], s[28:29], 0, v[210:211]
	s_mov_b64 s[18:19], 0x30000
	v_lshl_add_u64 v[124:125], s[42:43], 0, v[122:123]
	v_lshl_add_u64 v[126:127], s[54:55], 0, v[122:123]
	v_lshl_add_u64 v[130:131], v[130:131], 0, v[180:181]
	v_lshl_add_u64 v[132:133], v[132:133], 0, v[180:181]
	v_lshl_add_u64 v[192:193], v[208:209], 0, s[6:7]
	v_lshl_add_u64 v[190:191], v[208:209], 0, s[18:19]
	global_load_dwordx4 v[134:137], v[124:125], off offset:16
	global_load_dwordx4 v[142:145], v[124:125], off
	s_nop 0
	global_load_dwordx4 v[122:125], v[126:127], off offset:16
	s_nop 0
	global_load_dwordx4 v[126:129], v[126:127], off
	s_nop 0
	v_mov_b32_e32 v200, v218
	v_mov_b32_e32 v201, v219
	v_mov_b32_e32 v202, v220
	v_mov_b32_e32 v203, v221
	v_mov_b32_e32 v204, v222
	v_mov_b32_e32 v205, v223
	v_mov_b32_e32 v206, v224
	v_mov_b32_e32 v207, v225
	v_lshl_add_u64 v[130:131], s[28:29], 0, v[192:193]
	v_lshl_add_u64 v[132:133], s[28:29], 0, v[190:191]
	v_lshl_add_u64 v[130:131], v[130:131], 0, v[180:181]
	v_lshl_add_u64 v[132:133], v[132:133], 0, v[180:181]
	v_lshl_add_u64 v[188:189], v[208:209], 0, s[56:57]
	v_lshl_add_u64 v[186:187], v[208:209], 0, s[58:59]
	v_mov_b32_e32 v166, v226
	v_mov_b32_e32 v167, v227
	v_mov_b32_e32 v168, v228
	v_mov_b32_e32 v169, v229
	v_mov_b32_e32 v162, v230
	v_mov_b32_e32 v163, v231
	v_mov_b32_e32 v164, v232
	v_mov_b32_e32 v165, v233
	v_lshl_add_u64 v[130:131], s[28:29], 0, v[188:189]
	v_lshl_add_u64 v[132:133], s[28:29], 0, v[186:187]
	v_lshl_add_u64 v[130:131], v[130:131], 0, v[180:181]
	v_lshl_add_u64 v[132:133], v[132:133], 0, v[180:181]
	v_lshl_add_u64 v[184:185], v[208:209], 0, s[60:61]
	v_lshl_add_u64 v[182:183], v[208:209], 0, s[62:63]
	v_mov_b32_e32 v158, v234
	v_mov_b32_e32 v159, v235
	v_mov_b32_e32 v160, v236
	v_mov_b32_e32 v161, v237
	v_mov_b32_e32 v154, v238
	v_mov_b32_e32 v155, v239
	v_mov_b32_e32 v156, v240
	v_mov_b32_e32 v157, v241
	v_lshl_add_u64 v[130:131], s[28:29], 0, v[184:185]
	v_lshl_add_u64 v[132:133], s[28:29], 0, v[182:183]
	v_lshl_add_u64 v[130:131], v[130:131], 0, v[180:181]
	v_lshl_add_u64 v[132:133], v[132:133], 0, v[180:181]
	v_mov_b32_e32 v150, v242
	v_mov_b32_e32 v151, v243
	v_mov_b32_e32 v152, v244
	v_mov_b32_e32 v153, v245
	s_nop 0
	v_mov_b32_e32 v130, v246
	v_mov_b32_e32 v131, v247
	v_mov_b32_e32 v132, v248
	v_mov_b32_e32 v133, v249
	s_waitcnt vmcnt(0)
	v_add_f32_e32 v118, v118, v126
	v_add_f32_e32 v114, v114, v122
	v_mul_f32_e32 v118, 0xbfb8aa3b, v118
	v_mul_f32_e32 v114, 0xbfb8aa3b, v114
	v_exp_f32_e32 v118, v118
	v_exp_f32_e32 v199, v114
	v_add_f32_e32 v119, v119, v127
	v_add_f32_e32 v115, v115, v123
	v_mul_f32_e32 v119, 0xbfb8aa3b, v119
	v_mul_f32_e32 v115, 0xbfb8aa3b, v115
	v_add_f32_e32 v114, 1.0, v118
	v_add_f32_e32 v118, 1.0, v199
	v_exp_f32_e32 v119, v119
	v_exp_f32_e32 v199, v115
	v_add_f32_e32 v120, v120, v128
	v_add_f32_e32 v116, v116, v124
	v_mul_f32_e32 v120, 0xbfb8aa3b, v120
	v_mul_f32_e32 v116, 0xbfb8aa3b, v116
	v_add_f32_e32 v121, v121, v129
	v_add_f32_e32 v115, 1.0, v119
	v_add_f32_e32 v119, 1.0, v199
	v_exp_f32_e32 v120, v120
	v_exp_f32_e32 v199, v116
	v_mul_f32_e32 v121, 0xbfb8aa3b, v121
	v_exp_f32_e32 v121, v121
	v_add_f32_e32 v117, v117, v125
	v_mul_f32_e32 v117, 0xbfb8aa3b, v117
	v_add_f32_e32 v116, 1.0, v120
	v_add_f32_e32 v120, 1.0, v199
	v_exp_f32_e32 v199, v117
	v_add_f32_e32 v117, 1.0, v121
	v_rcp_f32_e32 v114, v114
	v_rcp_f32_e32 v115, v115
	v_rcp_f32_e32 v116, v116
	v_rcp_f32_e32 v117, v117
	v_rcp_f32_e32 v118, v118
	v_rcp_f32_e32 v119, v119
	v_add_f32_e32 v121, 1.0, v199
	v_pk_add_f32 v[148:149], v[148:149], v[144:145]
	v_pk_add_f32 v[146:147], v[146:147], v[142:143]
	v_rcp_f32_e32 v120, v120
	v_rcp_f32_e32 v121, v121
	v_and_b32_e32 v215, 0xffff0000, v200
	v_lshlrev_b32_e32 v214, 16, v200
	v_pk_mul_f32 v[114:115], v[146:147], v[114:115]
	v_and_b32_e32 v147, 0xffff0000, v201
	v_lshlrev_b32_e32 v146, 16, v201
	v_pk_mul_f32 v[116:117], v[148:149], v[116:117]
	v_pk_add_f32 v[138:139], v[138:139], v[134:135]
	v_pk_mul_f32 v[114:115], v[114:115], v[214:215]
	v_pk_mul_f32 v[116:117], v[116:117], v[146:147]
	v_pk_add_f32 v[140:141], v[140:141], v[136:137]
	v_cvt_pk_bf16_f32 v114, v114, v115
	v_cvt_pk_bf16_f32 v115, v116, v117
	v_and_b32_e32 v117, 0xffff0000, v202
	v_lshlrev_b32_e32 v116, 16, v202
	v_pk_mul_f32 v[118:119], v[138:139], v[118:119]
	v_pk_mul_f32 v[120:121], v[140:141], v[120:121]
	v_pk_mul_f32 v[116:117], v[118:119], v[116:117]
	v_and_b32_e32 v119, 0xffff0000, v203
	v_lshlrev_b32_e32 v118, 16, v203
	v_pk_mul_f32 v[118:119], v[120:121], v[118:119]
	v_cvt_pk_bf16_f32 v116, v116, v117
	v_cvt_pk_bf16_f32 v117, v118, v119
	v_lshl_add_u64 v[118:119], s[26:27], 0, v[208:209]
	v_add_f32_e32 v102, v102, v126
	v_add_f32_e32 v98, v98, v122
	v_lshl_add_u64 v[118:119], v[118:119], 0, v[180:181]
	v_mul_f32_e32 v102, 0xbfb8aa3b, v102
	v_mul_f32_e32 v98, 0xbfb8aa3b, v98
	global_store_dwordx4 v[118:119], v[114:117], off offset:2048
	v_exp_f32_e32 v102, v102
	v_add_f32_e32 v103, v103, v127
	v_exp_f32_e32 v114, v98
	v_add_f32_e32 v99, v99, v123
	v_mul_f32_e32 v103, 0xbfb8aa3b, v103
	v_mul_f32_e32 v99, 0xbfb8aa3b, v99
	v_add_f32_e32 v98, 1.0, v102
	v_add_f32_e32 v102, 1.0, v114
	v_exp_f32_e32 v103, v103
	v_exp_f32_e32 v114, v99
	v_add_f32_e32 v104, v104, v128
; __device__ __forceinline__ float fast_sigmoid(float v) { return __builtin_amdgcn_rcpf(1.f + __expf(-v)); }
; __device__ __forceinline__ u32x4 pack8(const f32x4 v0, const f32x4 v1) { u32x4 w; w.x = pk_f16(v0[0], v0[1]); w.y = pk_f16(v0[2], v0[3]); w.z = pk_f16(v1[0], v1[1]); w.w = pk_f16(v1[2], v1[3]); return w; }
; __device__ __forceinline__ void unpack8(const u32x4 w, f32x4& v0, f32x4& v1) { v0 = (f32x4){f16lo(w.x), f16hi(w.x), f16lo(w.y), f16hi(w.y)}; v1 = (f32x4){f16lo(w.z), f16hi(w.z), f16lo(w.w), f16hi(w.w)}; }
;     __device__ __forceinline__ void operator()(AccRef acc, const Unit& u, int wr, int wc, int fr, int fq) const {
;     ...
;             for (int m = 0; m < 4; ++m) { const size_t o = (size_t)(row0 + ai * HALF + m * 16) * D + PW + col0;
;                 f32x4 z0, z1; unpack8(zv[ai][m], z0, z1);
;                 f32x4 y10 = acc[ai][0][m][0] + b10, y11 = acc[ai][0][m][1] + b11, y20 = acc[ai][1][m][0] + b20, y21 = acc[ai][1][m][1] + b21;
; #pragma unroll
;                 for (int j = 0; j < 4; ++j) { y10[j] = y10[j] * fast_sigmoid(y20[j]) * z0[j]; y11[j] = y11[j] * fast_sigmoid(y21[j]) * z1[j]; }
;                 *(u32x4*)(branch + o) = pack8(y10, y11); }
	v_add_f32_e32 v100, v100, v124
	v_mul_f32_e32 v104, 0xbfb8aa3b, v104
	v_mul_f32_e32 v100, 0xbfb8aa3b, v100
	v_add_f32_e32 v105, v105, v129
	v_add_f32_e32 v99, 1.0, v103
	v_add_f32_e32 v103, 1.0, v114
	v_exp_f32_e32 v104, v104
	v_exp_f32_e32 v114, v100
	v_mul_f32_e32 v105, 0xbfb8aa3b, v105
	v_exp_f32_e32 v105, v105
	v_add_f32_e32 v101, v101, v125
	v_mul_f32_e32 v101, 0xbfb8aa3b, v101
	v_add_f32_e32 v100, 1.0, v104
	v_add_f32_e32 v104, 1.0, v114
	v_exp_f32_e32 v114, v101
	v_add_f32_e32 v101, 1.0, v105
	v_rcp_f32_e32 v98, v98
	v_rcp_f32_e32 v99, v99
	v_rcp_f32_e32 v100, v100
	v_rcp_f32_e32 v101, v101
	v_rcp_f32_e32 v102, v102
	v_rcp_f32_e32 v103, v103
	v_add_f32_e32 v105, 1.0, v114
	v_pk_add_f32 v[112:113], v[112:113], v[144:145]
	v_pk_add_f32 v[110:111], v[110:111], v[142:143]
	v_rcp_f32_e32 v104, v104
	v_rcp_f32_e32 v105, v105
	v_and_b32_e32 v115, 0xffff0000, v204
	v_lshlrev_b32_e32 v114, 16, v204
	v_pk_mul_f32 v[98:99], v[110:111], v[98:99]
	v_and_b32_e32 v111, 0xffff0000, v205
	v_lshlrev_b32_e32 v110, 16, v205
	v_pk_mul_f32 v[100:101], v[112:113], v[100:101]
	v_pk_add_f32 v[106:107], v[106:107], v[134:135]
	v_pk_mul_f32 v[98:99], v[98:99], v[114:115]
	v_pk_mul_f32 v[100:101], v[100:101], v[110:111]
	v_pk_add_f32 v[108:109], v[108:109], v[136:137]
	v_cvt_pk_bf16_f32 v98, v98, v99
	v_cvt_pk_bf16_f32 v99, v100, v101
	v_and_b32_e32 v101, 0xffff0000, v206
	v_lshlrev_b32_e32 v100, 16, v206
	v_pk_mul_f32 v[102:103], v[106:107], v[102:103]
	v_pk_mul_f32 v[104:105], v[108:109], v[104:105]
	v_pk_mul_f32 v[100:101], v[102:103], v[100:101]
	v_and_b32_e32 v103, 0xffff0000, v207
	v_lshlrev_b32_e32 v102, 16, v207
	v_pk_mul_f32 v[102:103], v[104:105], v[102:103]
	v_cvt_pk_bf16_f32 v100, v100, v101
	v_cvt_pk_bf16_f32 v101, v102, v103
	v_lshl_add_u64 v[102:103], s[26:27], 0, v[210:211]
	v_add_f32_e32 v86, v86, v126
	v_add_f32_e32 v82, v82, v122
	v_lshl_add_u64 v[102:103], v[102:103], 0, v[180:181]
	v_mul_f32_e32 v86, 0xbfb8aa3b, v86
	v_mul_f32_e32 v82, 0xbfb8aa3b, v82
	global_store_dwordx4 v[102:103], v[98:101], off offset:2048
	v_exp_f32_e32 v86, v86
	v_add_f32_e32 v87, v87, v127
	v_exp_f32_e32 v98, v82
	v_add_f32_e32 v83, v83, v123
	v_mul_f32_e32 v87, 0xbfb8aa3b, v87
	v_mul_f32_e32 v83, 0xbfb8aa3b, v83
	v_add_f32_e32 v82, 1.0, v86
	v_add_f32_e32 v86, 1.0, v98
	v_exp_f32_e32 v87, v87
	v_exp_f32_e32 v98, v83
	v_add_f32_e32 v88, v88, v128
	v_add_f32_e32 v84, v84, v124
	v_mul_f32_e32 v88, 0xbfb8aa3b, v88
	v_mul_f32_e32 v84, 0xbfb8aa3b, v84
	v_add_f32_e32 v89, v89, v129
	v_add_f32_e32 v83, 1.0, v87
	v_add_f32_e32 v87, 1.0, v98
	v_exp_f32_e32 v88, v88
	v_exp_f32_e32 v98, v84
	v_mul_f32_e32 v89, 0xbfb8aa3b, v89
	v_exp_f32_e32 v89, v89
	v_add_f32_e32 v85, v85, v125
	v_mul_f32_e32 v85, 0xbfb8aa3b, v85
	v_add_f32_e32 v84, 1.0, v88
	v_add_f32_e32 v88, 1.0, v98
	v_exp_f32_e32 v98, v85
	v_add_f32_e32 v85, 1.0, v89
	v_rcp_f32_e32 v82, v82
	v_rcp_f32_e32 v83, v83
	v_rcp_f32_e32 v84, v84
	v_rcp_f32_e32 v85, v85
	v_rcp_f32_e32 v86, v86
	v_rcp_f32_e32 v87, v87
	v_add_f32_e32 v89, 1.0, v98
	v_pk_add_f32 v[96:97], v[96:97], v[144:145]
	v_pk_add_f32 v[94:95], v[94:95], v[142:143]
	v_rcp_f32_e32 v88, v88
	v_rcp_f32_e32 v89, v89
	v_and_b32_e32 v99, 0xffff0000, v166
	v_lshlrev_b32_e32 v98, 16, v166
	v_pk_mul_f32 v[82:83], v[94:95], v[82:83]
	v_and_b32_e32 v95, 0xffff0000, v167
	v_lshlrev_b32_e32 v94, 16, v167
	v_pk_mul_f32 v[84:85], v[96:97], v[84:85]
	v_pk_add_f32 v[90:91], v[90:91], v[134:135]
	v_pk_mul_f32 v[82:83], v[82:83], v[98:99]
	v_pk_mul_f32 v[84:85], v[84:85], v[94:95]
	v_pk_add_f32 v[92:93], v[92:93], v[136:137]
	v_cvt_pk_bf16_f32 v82, v82, v83
	v_cvt_pk_bf16_f32 v83, v84, v85
	v_and_b32_e32 v85, 0xffff0000, v168
	v_lshlrev_b32_e32 v84, 16, v168
	v_pk_mul_f32 v[86:87], v[90:91], v[86:87]
	v_pk_mul_f32 v[88:89], v[92:93], v[88:89]
	v_pk_mul_f32 v[84:85], v[86:87], v[84:85]
	v_and_b32_e32 v87, 0xffff0000, v169
	v_lshlrev_b32_e32 v86, 16, v169
	v_pk_mul_f32 v[86:87], v[88:89], v[86:87]
	v_cvt_pk_bf16_f32 v84, v84, v85
	v_cvt_pk_bf16_f32 v85, v86, v87
	v_lshl_add_u64 v[86:87], s[26:27], 0, v[192:193]
	v_add_f32_e32 v70, v70, v126
	v_add_f32_e32 v66, v66, v122
	v_lshl_add_u64 v[86:87], v[86:87], 0, v[180:181]
	v_mul_f32_e32 v70, 0xbfb8aa3b, v70
	v_mul_f32_e32 v66, 0xbfb8aa3b, v66
	global_store_dwordx4 v[86:87], v[82:85], off offset:2048
	v_exp_f32_e32 v70, v70
	v_add_f32_e32 v71, v71, v127
	v_exp_f32_e32 v82, v66
	v_add_f32_e32 v67, v67, v123
	v_mul_f32_e32 v71, 0xbfb8aa3b, v71
	v_mul_f32_e32 v67, 0xbfb8aa3b, v67
	v_add_f32_e32 v66, 1.0, v70
	v_add_f32_e32 v70, 1.0, v82
	v_exp_f32_e32 v71, v71
	v_exp_f32_e32 v82, v67
	v_add_f32_e32 v72, v72, v128
	v_add_f32_e32 v68, v68, v124
	v_mul_f32_e32 v72, 0xbfb8aa3b, v72
	v_mul_f32_e32 v68, 0xbfb8aa3b, v68
	v_add_f32_e32 v73, v73, v129
	v_add_f32_e32 v67, 1.0, v71
	v_add_f32_e32 v71, 1.0, v82
	v_exp_f32_e32 v72, v72
	v_exp_f32_e32 v82, v68
	v_mul_f32_e32 v73, 0xbfb8aa3b, v73
	v_exp_f32_e32 v73, v73
	v_add_f32_e32 v69, v69, v125
	v_mul_f32_e32 v69, 0xbfb8aa3b, v69
	v_add_f32_e32 v68, 1.0, v72
	v_add_f32_e32 v72, 1.0, v82
	v_exp_f32_e32 v82, v69
	v_add_f32_e32 v69, 1.0, v73
	v_rcp_f32_e32 v66, v66
	v_rcp_f32_e32 v67, v67
	v_rcp_f32_e32 v68, v68
	v_rcp_f32_e32 v69, v69
	v_rcp_f32_e32 v70, v70
	v_rcp_f32_e32 v71, v71
	v_add_f32_e32 v73, 1.0, v82
	v_pk_add_f32 v[80:81], v[80:81], v[144:145]
	v_pk_add_f32 v[78:79], v[78:79], v[142:143]
	v_rcp_f32_e32 v72, v72
	v_rcp_f32_e32 v73, v73
	v_and_b32_e32 v83, 0xffff0000, v162
	v_lshlrev_b32_e32 v82, 16, v162
	v_pk_mul_f32 v[66:67], v[78:79], v[66:67]
	v_and_b32_e32 v79, 0xffff0000, v163
	v_lshlrev_b32_e32 v78, 16, v163
	v_pk_mul_f32 v[68:69], v[80:81], v[68:69]
	v_pk_add_f32 v[74:75], v[74:75], v[134:135]
; __device__ __forceinline__ float fast_sigmoid(float v) { return __builtin_amdgcn_rcpf(1.f + __expf(-v)); }
; __device__ __forceinline__ u32x4 pack8(const f32x4 v0, const f32x4 v1) { u32x4 w; w.x = pk_f16(v0[0], v0[1]); w.y = pk_f16(v0[2], v0[3]); w.z = pk_f16(v1[0], v1[1]); w.w = pk_f16(v1[2], v1[3]); return w; }
; __device__ __forceinline__ void unpack8(const u32x4 w, f32x4& v0, f32x4& v1) { v0 = (f32x4){f16lo(w.x), f16hi(w.x), f16lo(w.y), f16hi(w.y)}; v1 = (f32x4){f16lo(w.z), f16hi(w.z), f16lo(w.w), f16hi(w.w)}; }
;     __device__ __forceinline__ void operator()(AccRef acc, const Unit& u, int wr, int wc, int fr, int fq) const {
;     ...
;             for (int m = 0; m < 4; ++m) { const size_t o = (size_t)(row0 + ai * HALF + m * 16) * D + PW + col0;
;                 f32x4 z0, z1; unpack8(zv[ai][m], z0, z1);
;                 f32x4 y10 = acc[ai][0][m][0] + b10, y11 = acc[ai][0][m][1] + b11, y20 = acc[ai][1][m][0] + b20, y21 = acc[ai][1][m][1] + b21;
; #pragma unroll
;                 for (int j = 0; j < 4; ++j) { y10[j] = y10[j] * fast_sigmoid(y20[j]) * z0[j]; y11[j] = y11[j] * fast_sigmoid(y21[j]) * z1[j]; }
;                 *(u32x4*)(branch + o) = pack8(y10, y11); }
	v_pk_mul_f32 v[66:67], v[66:67], v[82:83]
	v_pk_mul_f32 v[68:69], v[68:69], v[78:79]
	v_pk_add_f32 v[76:77], v[76:77], v[136:137]
	v_cvt_pk_bf16_f32 v66, v66, v67
	v_cvt_pk_bf16_f32 v67, v68, v69
	v_and_b32_e32 v69, 0xffff0000, v164
	v_lshlrev_b32_e32 v68, 16, v164
	v_pk_mul_f32 v[70:71], v[74:75], v[70:71]
	v_pk_mul_f32 v[72:73], v[76:77], v[72:73]
	v_pk_mul_f32 v[68:69], v[70:71], v[68:69]
	v_and_b32_e32 v71, 0xffff0000, v165
	v_lshlrev_b32_e32 v70, 16, v165
	v_pk_mul_f32 v[70:71], v[72:73], v[70:71]
	v_cvt_pk_bf16_f32 v68, v68, v69
	v_cvt_pk_bf16_f32 v69, v70, v71
	v_lshl_add_u64 v[70:71], s[26:27], 0, v[190:191]
	v_add_f32_e32 v54, v54, v126
	v_add_f32_e32 v50, v50, v122
	v_lshl_add_u64 v[70:71], v[70:71], 0, v[180:181]
	v_mul_f32_e32 v54, 0xbfb8aa3b, v54
	v_mul_f32_e32 v50, 0xbfb8aa3b, v50
	global_store_dwordx4 v[70:71], v[66:69], off offset:2048
	v_exp_f32_e32 v54, v54
	v_add_f32_e32 v55, v55, v127
	v_exp_f32_e32 v66, v50
	v_add_f32_e32 v51, v51, v123
	v_mul_f32_e32 v55, 0xbfb8aa3b, v55
	v_mul_f32_e32 v51, 0xbfb8aa3b, v51
	v_add_f32_e32 v50, 1.0, v54
	v_add_f32_e32 v54, 1.0, v66
	v_exp_f32_e32 v55, v55
	v_exp_f32_e32 v66, v51
	v_add_f32_e32 v56, v56, v128
	v_add_f32_e32 v52, v52, v124
	v_mul_f32_e32 v56, 0xbfb8aa3b, v56
	v_mul_f32_e32 v52, 0xbfb8aa3b, v52
	v_add_f32_e32 v57, v57, v129
	v_add_f32_e32 v51, 1.0, v55
	v_add_f32_e32 v55, 1.0, v66
	v_exp_f32_e32 v56, v56
	v_exp_f32_e32 v66, v52
	v_mul_f32_e32 v57, 0xbfb8aa3b, v57
	v_exp_f32_e32 v57, v57
	v_add_f32_e32 v53, v53, v125
	v_mul_f32_e32 v53, 0xbfb8aa3b, v53
	v_add_f32_e32 v52, 1.0, v56
	v_add_f32_e32 v56, 1.0, v66
	v_exp_f32_e32 v66, v53
	v_add_f32_e32 v53, 1.0, v57
	v_rcp_f32_e32 v50, v50
	v_rcp_f32_e32 v51, v51
	v_rcp_f32_e32 v52, v52
	v_rcp_f32_e32 v53, v53
	v_rcp_f32_e32 v54, v54
	v_rcp_f32_e32 v55, v55
	v_add_f32_e32 v57, 1.0, v66
	v_pk_add_f32 v[64:65], v[64:65], v[144:145]
	v_pk_add_f32 v[62:63], v[62:63], v[142:143]
	v_rcp_f32_e32 v56, v56
	v_rcp_f32_e32 v57, v57
	v_and_b32_e32 v67, 0xffff0000, v158
	v_lshlrev_b32_e32 v66, 16, v158
	v_pk_mul_f32 v[50:51], v[62:63], v[50:51]
	v_and_b32_e32 v63, 0xffff0000, v159
	v_lshlrev_b32_e32 v62, 16, v159
	v_pk_mul_f32 v[52:53], v[64:65], v[52:53]
	v_pk_add_f32 v[58:59], v[58:59], v[134:135]
	v_pk_mul_f32 v[50:51], v[50:51], v[66:67]
	v_pk_mul_f32 v[52:53], v[52:53], v[62:63]
	v_pk_add_f32 v[60:61], v[60:61], v[136:137]
	v_cvt_pk_bf16_f32 v50, v50, v51
	v_cvt_pk_bf16_f32 v51, v52, v53
	v_and_b32_e32 v53, 0xffff0000, v160
	v_lshlrev_b32_e32 v52, 16, v160
	v_pk_mul_f32 v[54:55], v[58:59], v[54:55]
	v_pk_mul_f32 v[56:57], v[60:61], v[56:57]
	v_pk_mul_f32 v[52:53], v[54:55], v[52:53]
	v_and_b32_e32 v55, 0xffff0000, v161
	v_lshlrev_b32_e32 v54, 16, v161
	v_pk_mul_f32 v[54:55], v[56:57], v[54:55]
	v_cvt_pk_bf16_f32 v52, v52, v53
	v_cvt_pk_bf16_f32 v53, v54, v55
	v_lshl_add_u64 v[54:55], s[26:27], 0, v[188:189]
	v_add_f32_e32 v38, v38, v126
	v_add_f32_e32 v34, v34, v122
	v_lshl_add_u64 v[54:55], v[54:55], 0, v[180:181]
	v_mul_f32_e32 v38, 0xbfb8aa3b, v38
	v_mul_f32_e32 v34, 0xbfb8aa3b, v34
	global_store_dwordx4 v[54:55], v[50:53], off offset:2048
	v_exp_f32_e32 v38, v38
	v_add_f32_e32 v39, v39, v127
	v_exp_f32_e32 v50, v34
	v_add_f32_e32 v35, v35, v123
	v_mul_f32_e32 v39, 0xbfb8aa3b, v39
	v_mul_f32_e32 v35, 0xbfb8aa3b, v35
	v_add_f32_e32 v34, 1.0, v38
	v_add_f32_e32 v38, 1.0, v50
	v_exp_f32_e32 v39, v39
	v_exp_f32_e32 v50, v35
	v_add_f32_e32 v40, v40, v128
	v_add_f32_e32 v36, v36, v124
	v_mul_f32_e32 v40, 0xbfb8aa3b, v40
	v_mul_f32_e32 v36, 0xbfb8aa3b, v36
	v_add_f32_e32 v41, v41, v129
	v_add_f32_e32 v35, 1.0, v39
	v_add_f32_e32 v39, 1.0, v50
	v_exp_f32_e32 v40, v40
	v_exp_f32_e32 v50, v36
	v_mul_f32_e32 v41, 0xbfb8aa3b, v41
	v_exp_f32_e32 v41, v41
	v_add_f32_e32 v37, v37, v125
	v_mul_f32_e32 v37, 0xbfb8aa3b, v37
	v_add_f32_e32 v36, 1.0, v40
	v_add_f32_e32 v40, 1.0, v50
	v_exp_f32_e32 v50, v37
	v_add_f32_e32 v37, 1.0, v41
	v_rcp_f32_e32 v34, v34
	v_rcp_f32_e32 v35, v35
	v_rcp_f32_e32 v36, v36
	v_rcp_f32_e32 v37, v37
	v_rcp_f32_e32 v38, v38
	v_rcp_f32_e32 v39, v39
	v_add_f32_e32 v41, 1.0, v50
	v_pk_add_f32 v[48:49], v[48:49], v[144:145]
	v_pk_add_f32 v[46:47], v[46:47], v[142:143]
	v_rcp_f32_e32 v40, v40
	v_rcp_f32_e32 v41, v41
	v_and_b32_e32 v51, 0xffff0000, v154
	v_lshlrev_b32_e32 v50, 16, v154
	v_pk_mul_f32 v[34:35], v[46:47], v[34:35]
	v_and_b32_e32 v47, 0xffff0000, v155
	v_lshlrev_b32_e32 v46, 16, v155
	v_pk_mul_f32 v[36:37], v[48:49], v[36:37]
	v_pk_add_f32 v[42:43], v[42:43], v[134:135]
	v_pk_mul_f32 v[34:35], v[34:35], v[50:51]
	v_pk_mul_f32 v[36:37], v[36:37], v[46:47]
	v_pk_add_f32 v[44:45], v[44:45], v[136:137]
	v_cvt_pk_bf16_f32 v34, v34, v35
	v_cvt_pk_bf16_f32 v35, v36, v37
	v_and_b32_e32 v37, 0xffff0000, v156
	v_lshlrev_b32_e32 v36, 16, v156
	v_pk_mul_f32 v[38:39], v[42:43], v[38:39]
	v_pk_mul_f32 v[40:41], v[44:45], v[40:41]
	v_pk_mul_f32 v[36:37], v[38:39], v[36:37]
	v_and_b32_e32 v39, 0xffff0000, v157
	v_lshlrev_b32_e32 v38, 16, v157
	v_pk_mul_f32 v[38:39], v[40:41], v[38:39]
	v_cvt_pk_bf16_f32 v36, v36, v37
	v_cvt_pk_bf16_f32 v37, v38, v39
	v_lshl_add_u64 v[38:39], s[26:27], 0, v[186:187]
	v_add_f32_e32 v22, v22, v126
	v_add_f32_e32 v18, v18, v122
	v_lshl_add_u64 v[38:39], v[38:39], 0, v[180:181]
	v_mul_f32_e32 v22, 0xbfb8aa3b, v22
	v_mul_f32_e32 v18, 0xbfb8aa3b, v18
	global_store_dwordx4 v[38:39], v[34:37], off offset:2048
	v_exp_f32_e32 v22, v22
	v_add_f32_e32 v23, v23, v127
; __device__ __forceinline__ float fast_sigmoid(float v) { return __builtin_amdgcn_rcpf(1.f + __expf(-v)); }
; #define PG8_BAR __builtin_amdgcn_s_barrier()
; __device__ __forceinline__ u32x4 pack8(const f32x4 v0, const f32x4 v1) { u32x4 w; w.x = pk_f16(v0[0], v0[1]); w.y = pk_f16(v0[2], v0[3]); w.z = pk_f16(v1[0], v1[1]); w.w = pk_f16(v1[2], v1[3]); return w; }
; __device__ __forceinline__ void unpack8(const u32x4 w, f32x4& v0, f32x4& v1) { v0 = (f32x4){f16lo(w.x), f16hi(w.x), f16lo(w.y), f16hi(w.y)}; v1 = (f32x4){f16lo(w.z), f16hi(w.z), f16lo(w.w), f16hi(w.w)}; }
; template <class CF, class Epi, class Sched, bool ALIGN_EPI, bool SP2>
; __device__ __forceinline__ void gemm_phase(LAS unsigned char* lds, const char* gA, const char* gB, const Sched& S, const Epi& E, const char* gB2 = nullptr) {
;     ...
;         if (!has_next) break;
; #pragma unroll
;         for (int a = 0; a < 2; ++a)
; #pragma unroll
;             for (int b = 0; b < 2; ++b)
; #pragma unroll
;                 for (int m = 0; m < 4; ++m)
; #pragma unroll
;                     for (int n = 0; n < 2; ++n) acc[a][b][m][n] = (f32x4){0.f, 0.f, 0.f, 0.f};
;         cur = nxt; cA = nA; cB = nB; ++ui;
;         if constexpr (BMODE == 1) cT = gB2 + (size_t)cur.g * KTG + (size_t)cur.pn * 8192 + 14336;
;         if constexpr (ALIGN_EPI) { if (wr == 1) PG8_BAR; }
;     }
;     __device__ __forceinline__ void operator()(AccRef acc, const Unit& u, int wr, int wc, int fr, int fq) const {
;     ...
;             for (int m = 0; m < 4; ++m) { const size_t o = (size_t)(row0 + ai * HALF + m * 16) * D + PW + col0;
;                 f32x4 z0, z1; unpack8(zv[ai][m], z0, z1);
;                 f32x4 y10 = acc[ai][0][m][0] + b10, y11 = acc[ai][0][m][1] + b11, y20 = acc[ai][1][m][0] + b20, y21 = acc[ai][1][m][1] + b21;
; #pragma unroll
;                 for (int j = 0; j < 4; ++j) { y10[j] = y10[j] * fast_sigmoid(y20[j]) * z0[j]; y11[j] = y11[j] * fast_sigmoid(y21[j]) * z1[j]; }
;                 *(u32x4*)(branch + o) = pack8(y10, y11); }
	v_exp_f32_e32 v34, v18
	v_add_f32_e32 v19, v19, v123
	v_mul_f32_e32 v23, 0xbfb8aa3b, v23
	v_mul_f32_e32 v19, 0xbfb8aa3b, v19
	v_add_f32_e32 v18, 1.0, v22
	v_add_f32_e32 v22, 1.0, v34
	v_exp_f32_e32 v23, v23
	v_exp_f32_e32 v34, v19
	v_add_f32_e32 v24, v24, v128
	v_add_f32_e32 v20, v20, v124
	v_mul_f32_e32 v24, 0xbfb8aa3b, v24
	v_mul_f32_e32 v20, 0xbfb8aa3b, v20
	v_add_f32_e32 v25, v25, v129
	v_add_f32_e32 v19, 1.0, v23
	v_add_f32_e32 v23, 1.0, v34
	v_exp_f32_e32 v24, v24
	v_exp_f32_e32 v34, v20
	v_mul_f32_e32 v25, 0xbfb8aa3b, v25
	v_exp_f32_e32 v25, v25
	v_add_f32_e32 v21, v21, v125
	v_mul_f32_e32 v21, 0xbfb8aa3b, v21
	v_add_f32_e32 v20, 1.0, v24
	v_add_f32_e32 v24, 1.0, v34
	v_exp_f32_e32 v34, v21
	v_add_f32_e32 v21, 1.0, v25
	v_rcp_f32_e32 v18, v18
	v_rcp_f32_e32 v19, v19
	v_rcp_f32_e32 v20, v20
	v_rcp_f32_e32 v21, v21
	v_rcp_f32_e32 v22, v22
	v_rcp_f32_e32 v23, v23
	v_add_f32_e32 v25, 1.0, v34
	v_pk_add_f32 v[32:33], v[32:33], v[144:145]
	v_pk_add_f32 v[30:31], v[30:31], v[142:143]
	v_rcp_f32_e32 v24, v24
	v_rcp_f32_e32 v25, v25
	v_and_b32_e32 v35, 0xffff0000, v150
	v_lshlrev_b32_e32 v34, 16, v150
	v_pk_mul_f32 v[18:19], v[30:31], v[18:19]
	v_and_b32_e32 v31, 0xffff0000, v151
	v_lshlrev_b32_e32 v30, 16, v151
	v_pk_mul_f32 v[20:21], v[32:33], v[20:21]
	v_pk_add_f32 v[26:27], v[26:27], v[134:135]
	v_pk_mul_f32 v[18:19], v[18:19], v[34:35]
	v_pk_mul_f32 v[20:21], v[20:21], v[30:31]
	v_pk_add_f32 v[28:29], v[28:29], v[136:137]
	v_cvt_pk_bf16_f32 v18, v18, v19
	v_cvt_pk_bf16_f32 v19, v20, v21
	v_and_b32_e32 v21, 0xffff0000, v152
	v_lshlrev_b32_e32 v20, 16, v152
	v_pk_mul_f32 v[22:23], v[26:27], v[22:23]
	v_pk_mul_f32 v[24:25], v[28:29], v[24:25]
	v_pk_mul_f32 v[20:21], v[22:23], v[20:21]
	v_and_b32_e32 v23, 0xffff0000, v153
	v_lshlrev_b32_e32 v22, 16, v153
	v_pk_mul_f32 v[22:23], v[24:25], v[22:23]
	v_cvt_pk_bf16_f32 v20, v20, v21
	v_cvt_pk_bf16_f32 v21, v22, v23
	v_lshl_add_u64 v[22:23], s[26:27], 0, v[184:185]
	v_add_f32_e32 v6, v6, v126
	v_add_f32_e32 v2, v2, v122
	v_lshl_add_u64 v[22:23], v[22:23], 0, v[180:181]
	v_mul_f32_e32 v6, 0xbfb8aa3b, v6
	v_mul_f32_e32 v2, 0xbfb8aa3b, v2
	global_store_dwordx4 v[22:23], v[18:21], off offset:2048
	v_exp_f32_e32 v6, v6
	v_add_f32_e32 v7, v7, v127
	v_exp_f32_e32 v18, v2
	v_add_f32_e32 v3, v3, v123
	v_mul_f32_e32 v7, 0xbfb8aa3b, v7
	v_mul_f32_e32 v3, 0xbfb8aa3b, v3
	v_add_f32_e32 v2, 1.0, v6
	v_add_f32_e32 v6, 1.0, v18
	v_exp_f32_e32 v7, v7
	v_exp_f32_e32 v18, v3
	v_add_f32_e32 v8, v8, v128
	v_add_f32_e32 v4, v4, v124
	v_mul_f32_e32 v8, 0xbfb8aa3b, v8
	v_mul_f32_e32 v4, 0xbfb8aa3b, v4
	v_add_f32_e32 v9, v9, v129
	v_add_f32_e32 v3, 1.0, v7
	v_add_f32_e32 v7, 1.0, v18
	v_exp_f32_e32 v8, v8
	v_exp_f32_e32 v18, v4
	v_mul_f32_e32 v9, 0xbfb8aa3b, v9
	v_exp_f32_e32 v9, v9
	v_add_f32_e32 v5, v5, v125
	v_mul_f32_e32 v5, 0xbfb8aa3b, v5
	v_add_f32_e32 v4, 1.0, v8
	v_add_f32_e32 v8, 1.0, v18
	v_exp_f32_e32 v18, v5
	v_add_f32_e32 v5, 1.0, v9
	v_rcp_f32_e32 v2, v2
	v_rcp_f32_e32 v3, v3
	v_rcp_f32_e32 v4, v4
	v_rcp_f32_e32 v5, v5
	v_rcp_f32_e32 v6, v6
	v_rcp_f32_e32 v7, v7
	v_add_f32_e32 v9, 1.0, v18
	v_pk_add_f32 v[16:17], v[16:17], v[144:145]
	v_pk_add_f32 v[14:15], v[14:15], v[142:143]
	v_rcp_f32_e32 v8, v8
	v_rcp_f32_e32 v9, v9
	v_and_b32_e32 v19, 0xffff0000, v130
	v_lshlrev_b32_e32 v18, 16, v130
	v_pk_mul_f32 v[2:3], v[14:15], v[2:3]
	v_and_b32_e32 v15, 0xffff0000, v131
	v_lshlrev_b32_e32 v14, 16, v131
	v_pk_mul_f32 v[4:5], v[16:17], v[4:5]
	v_pk_add_f32 v[10:11], v[10:11], v[134:135]
	v_pk_mul_f32 v[2:3], v[2:3], v[18:19]
	v_pk_mul_f32 v[4:5], v[4:5], v[14:15]
	v_pk_add_f32 v[12:13], v[12:13], v[136:137]
	v_cvt_pk_bf16_f32 v2, v2, v3
	v_cvt_pk_bf16_f32 v3, v4, v5
	v_and_b32_e32 v5, 0xffff0000, v132
	v_lshlrev_b32_e32 v4, 16, v132
	v_pk_mul_f32 v[6:7], v[10:11], v[6:7]
	v_pk_mul_f32 v[8:9], v[12:13], v[8:9]
	v_pk_mul_f32 v[4:5], v[6:7], v[4:5]
	v_and_b32_e32 v7, 0xffff0000, v133
	v_lshlrev_b32_e32 v6, 16, v133
	v_pk_mul_f32 v[6:7], v[8:9], v[6:7]
	v_cvt_pk_bf16_f32 v4, v4, v5
	v_cvt_pk_bf16_f32 v5, v6, v7
	v_lshl_add_u64 v[6:7], s[26:27], 0, v[182:183]
	v_lshl_add_u64 v[6:7], v[6:7], 0, v[180:181]
	s_and_b64 vcc, exec, s[2:3]
	s_cbranch_vccz .Lp6_nopre
	v_lshl_add_u32 v250, s66, 8, v1
	v_lshl_or_b32 v252, s64, 7, v195
	v_lshlrev_b32_e32 v250, 12, v250
	v_lshl_add_u32 v250, v252, 1, v250
	global_load_dwordx4 v[218:221], v250, s[28:29] offset:2048
	s_add_u32 s98, s28, 0x10000
	s_addc_u32 s99, s29, 0
	global_load_dwordx4 v[222:225], v250, s[98:99] offset:2048
	s_add_u32 s98, s28, 0x20000
	s_addc_u32 s99, s29, 0
	global_load_dwordx4 v[226:229], v250, s[98:99] offset:2048
	s_add_u32 s98, s28, 0x30000
	s_addc_u32 s99, s29, 0
	global_load_dwordx4 v[230:233], v250, s[98:99] offset:2048
	s_add_u32 s98, s28, 0x80000
	s_addc_u32 s99, s29, 0
	global_load_dwordx4 v[234:237], v250, s[98:99] offset:2048
	s_add_u32 s98, s28, 0x90000
	s_addc_u32 s99, s29, 0
	global_load_dwordx4 v[238:241], v250, s[98:99] offset:2048
	s_add_u32 s98, s28, 0xa0000
	s_addc_u32 s99, s29, 0
	global_load_dwordx4 v[242:245], v250, s[98:99] offset:2048
	s_add_u32 s98, s28, 0xb0000
	s_addc_u32 s99, s29, 0
	global_load_dwordx4 v[246:249], v250, s[98:99] offset:2048
.Lp6_nopre:
	s_andn2_b64 vcc, exec, s[2:3]
	s_mov_b64 s[2:3], -1
	global_store_dwordx4 v[6:7], v[2:5], off offset:2048
	s_cbranch_vccnz .LBB0_1062
	s_andn2_b64 vcc, exec, s[24:25]
	s_cbranch_vccnz .LBB0_1061
	s_barrier
	s_branch .LBB0_1061
